# drain every wave's stores before the cooperative grid sync's workgroup barrier (visibility hardening of the P0->P1 handoff)
# speedup vs baseline: 1.0035x; 1.0004x over previous
; __global__ void __launch_bounds__(512, 2) fwd_megakernel(Params p) {
;     ...
;     grid.sync();
.LBB0_1353:
	s_or_b64 exec, exec, s[8:9]
	v_lshrrev_b32_e32 v1, 20, v0
	v_lshrrev_b32_e32 v0, 10, v0
	v_or_b32_e32 v0, v0, v1
	s_movk_i32 s8, 0x3ff
	v_and_or_b32 v0, v0, s8, v198
	v_cmp_eq_u32_e32 vcc, 0, v0
	s_waitcnt vmcnt(0) lgkmcnt(0)
	s_barrier
	s_and_saveexec_b64 s[8:9], vcc
	s_cbranch_execz .LBB0_1363
	buffer_wbl2 sc1
	s_waitcnt vmcnt(0)
	s_load_dwordx2 s[2:3], s[2:3], 0x58
	v_mov_b32_e32 v2, 0
	s_mov_b64 s[10:11], exec
	v_mbcnt_lo_u32_b32 v1, s10, 0
	v_mbcnt_hi_u32_b32 v1, s11, v1
	s_waitcnt lgkmcnt(0)
	global_load_dword v0, v2, s[2:3] offset:40
	v_cmp_eq_u32_e32 vcc, 0, v1
	s_and_saveexec_b64 s[12:13], vcc
	s_cbranch_execz .LBB0_1356
	s_bcnt1_i32_b64 s10, s[10:11]
	v_mov_b32_e32 v3, s10
	global_atomic_add v3, v2, v3, s[2:3] offset:32 sc0
